# ada_tile output loop: the loop-invariant bias load is issued once before the loop, so iterations no longer wait on vmcnt(0) behind the previous store
# speedup vs baseline: 1.0040x; 1.0026x over previous
; DI void ada_tile(const Params& p, int layer, int cg64, char* lds) {
;     ...
; #pragma unroll 8
;   for (int kk = 0; kk < 256; ++kk) {
;     int k = kq * 256 + kk;
;     float wv = w[(size_t)k * 6144];
; #pragma unroll
;     for (int i = 0; i < 17; ++i) acc[i] += sc[i * 1024 + k] * wv;
;   }
.Lada_nopf:
	v_add_u32_e32 v96, s12, v74
	v_add_u32_e32 v114, 0x10000, v96
	s_mov_b64 s[14:15], 0x30000
	ds_read_b64 v[0:1], v96
	ds_read_b64 v[2:3], v96 offset:4096
	ds_read_b64 v[4:5], v96 offset:8192
	ds_read_b64 v[6:7], v96 offset:12288
	ds_read_b64 v[8:9], v96 offset:16384
	ds_read_b64 v[10:11], v96 offset:20480
	ds_read_b64 v[14:15], v96 offset:24576
	ds_read_b64 v[16:17], v96 offset:28672
	ds_read_b64 v[18:19], v96 offset:32768
	ds_read_b64 v[22:23], v96 offset:36864
	ds_read_b64 v[24:25], v96 offset:40960
	ds_read_b64 v[26:27], v96 offset:45056
	ds_read_b64 v[30:31], v96 offset:49152
	ds_read_b64 v[32:33], v96 offset:53248
	ds_read_b64 v[34:35], v96 offset:57344
	ds_read_b64 v[38:39], v96 offset:61440
	ds_read_b64 v[40:41], v114
	ds_read_b64 v[42:43], v96 offset:8
	ds_read_b64 v[46:47], v96 offset:4104
	ds_read_b64 v[48:49], v96 offset:8200
	ds_read_b64 v[50:51], v96 offset:12296
	ds_read_b64 v[54:55], v96 offset:16392
	ds_read_b64 v[56:57], v96 offset:20488
	ds_read_b64 v[58:59], v96 offset:24584
	ds_read_b64 v[62:63], v96 offset:28680
	ds_read_b64 v[64:65], v96 offset:32776
	ds_read_b64 v[66:67], v96 offset:36872
	ds_read_b64 v[70:71], v96 offset:40968
	ds_read_b64 v[98:99], v96 offset:45064
	ds_read_b64 v[100:101], v96 offset:49160
	ds_read_b64 v[102:103], v96 offset:53256
	ds_read_b64 v[104:105], v96 offset:57352
	ds_read_b64 v[106:107], v96 offset:61448
	ds_read_b64 v[108:109], v114 offset:8
	s_waitcnt lgkmcnt(15)
	v_fmac_f32_e32 v12, v116, v0
	v_fmac_f32_e32 v13, v116, v2
	v_fmac_f32_e32 v20, v116, v4
	v_fmac_f32_e32 v21, v116, v6
	v_fmac_f32_e32 v28, v116, v8
	v_fmac_f32_e32 v29, v116, v10
	v_fmac_f32_e32 v36, v116, v14
	v_fmac_f32_e32 v37, v116, v16
	v_fmac_f32_e32 v44, v116, v18
	v_fmac_f32_e32 v45, v116, v22
	v_fmac_f32_e32 v52, v116, v24
	v_fmac_f32_e32 v53, v116, v26
	v_fmac_f32_e32 v60, v116, v30
	v_fmac_f32_e32 v61, v116, v32
	v_fmac_f32_e32 v68, v116, v34
	v_fmac_f32_e32 v69, v116, v38
	v_fmac_f32_e32 v81, v116, v40
	v_fmac_f32_e32 v12, v117, v1
	v_fmac_f32_e32 v13, v117, v3
	v_fmac_f32_e32 v20, v117, v5
	v_fmac_f32_e32 v21, v117, v7
	v_fmac_f32_e32 v28, v117, v9
	v_fmac_f32_e32 v29, v117, v11
	v_fmac_f32_e32 v36, v117, v15
	v_fmac_f32_e32 v37, v117, v17
	v_fmac_f32_e32 v44, v117, v19
	v_fmac_f32_e32 v45, v117, v23
	v_fmac_f32_e32 v52, v117, v25
	v_fmac_f32_e32 v53, v117, v27
	v_fmac_f32_e32 v60, v117, v31
	v_fmac_f32_e32 v61, v117, v33
	v_fmac_f32_e32 v68, v117, v35
	v_fmac_f32_e32 v69, v117, v39
	v_fmac_f32_e32 v81, v117, v41
	ds_read_b64 v[0:1], v96 offset:16
	ds_read_b64 v[2:3], v96 offset:4112
	ds_read_b64 v[4:5], v96 offset:8208
	ds_read_b64 v[6:7], v96 offset:12304
	ds_read_b64 v[8:9], v96 offset:16400
	ds_read_b64 v[10:11], v96 offset:20496
	ds_read_b64 v[14:15], v96 offset:24592
	ds_read_b64 v[16:17], v96 offset:28688
	ds_read_b64 v[18:19], v96 offset:32784
	ds_read_b64 v[22:23], v96 offset:36880
	ds_read_b64 v[24:25], v96 offset:40976
	ds_read_b64 v[26:27], v96 offset:45072
	ds_read_b64 v[30:31], v96 offset:49168
	ds_read_b64 v[32:33], v96 offset:53264
	ds_read_b64 v[34:35], v96 offset:57360
	ds_read_b64 v[38:39], v96 offset:61456
	ds_read_b64 v[40:41], v114 offset:16
	s_waitcnt lgkmcnt(15)
	v_fmac_f32_e32 v12, v118, v42
	v_fmac_f32_e32 v13, v118, v46
	v_fmac_f32_e32 v20, v118, v48
	v_fmac_f32_e32 v21, v118, v50
	v_fmac_f32_e32 v28, v118, v54
	v_fmac_f32_e32 v29, v118, v56
	v_fmac_f32_e32 v36, v118, v58
	v_fmac_f32_e32 v37, v118, v62
	v_fmac_f32_e32 v44, v118, v64
	v_fmac_f32_e32 v45, v118, v66
	v_fmac_f32_e32 v52, v118, v70
	v_fmac_f32_e32 v53, v118, v98
	v_fmac_f32_e32 v60, v118, v100
	v_fmac_f32_e32 v61, v118, v102
	v_fmac_f32_e32 v68, v118, v104
	v_fmac_f32_e32 v69, v118, v106
	v_fmac_f32_e32 v81, v118, v108
	v_fmac_f32_e32 v12, v119, v43
	v_fmac_f32_e32 v13, v119, v47
	v_fmac_f32_e32 v20, v119, v49
	v_fmac_f32_e32 v21, v119, v51
	v_fmac_f32_e32 v28, v119, v55
	v_fmac_f32_e32 v29, v119, v57
	v_fmac_f32_e32 v36, v119, v59
	v_fmac_f32_e32 v37, v119, v63
	v_fmac_f32_e32 v44, v119, v65
	v_fmac_f32_e32 v45, v119, v67
	v_fmac_f32_e32 v52, v119, v71
	v_fmac_f32_e32 v53, v119, v99
	v_fmac_f32_e32 v60, v119, v101
	v_fmac_f32_e32 v61, v119, v103
	v_fmac_f32_e32 v68, v119, v105
	v_fmac_f32_e32 v69, v119, v107
	v_fmac_f32_e32 v81, v119, v109
	ds_read_b64 v[42:43], v96 offset:24
	ds_read_b64 v[46:47], v96 offset:4120
	ds_read_b64 v[48:49], v96 offset:8216
	ds_read_b64 v[50:51], v96 offset:12312
	ds_read_b64 v[54:55], v96 offset:16408
	ds_read_b64 v[56:57], v96 offset:20504
	ds_read_b64 v[58:59], v96 offset:24600
	ds_read_b64 v[62:63], v96 offset:28696
	ds_read_b64 v[64:65], v96 offset:32792
	ds_read_b64 v[66:67], v96 offset:36888
	ds_read_b64 v[70:71], v96 offset:40984
	ds_read_b64 v[98:99], v96 offset:45080
	ds_read_b64 v[100:101], v96 offset:49176
	ds_read_b64 v[102:103], v96 offset:53272
	ds_read_b64 v[104:105], v96 offset:57368
	ds_read_b64 v[106:107], v96 offset:61464
	ds_read_b64 v[108:109], v114 offset:24
	s_waitcnt lgkmcnt(15)
; DI void ada_tile(const Params& p, int layer, int cg64, char* lds) {
;     ...
;   for (int kk = 0; kk < 256; ++kk) {
;     int k = kq * 256 + kk;
;     float wv = w[(size_t)k * 6144];
; #pragma unroll
;     for (int i = 0; i < 17; ++i) acc[i] += sc[i * 1024 + k] * wv;
;   }
;   __syncthreads();
;   float* red = (float*)lds;
; #pragma unroll
;   for (int i = 0; i < 17; ++i) red[(kq * 17 + i) * 64 + col] = acc[i];
;   __syncthreads();
;   float* mod = (float*)(p.ws + O_MOD) + (size_t)layer * 17 * 6144;
;   for (int e = tid; e < 17 * 64; e += 256) {
;     int bi = e >> 6, cc = e & 63;
;     float s = red[(0 * 17 + bi) * 64 + cc] + red[(1 * 17 + bi) * 64 + cc] + red[(2 * 17 + bi) * 64 + cc] +
;               red[(3 * 17 + bi) * 64 + cc];
;     int nn = cg64 * 64 + cc;
;     mod[bi * 6144 + nn] = s + p.ada_b[layer * 6144 + nn];
;   }
	v_fmac_f32_e32 v12, v120, v0
	v_fmac_f32_e32 v13, v120, v2
	v_fmac_f32_e32 v20, v120, v4
	v_fmac_f32_e32 v21, v120, v6
	v_fmac_f32_e32 v28, v120, v8
	v_fmac_f32_e32 v29, v120, v10
	v_fmac_f32_e32 v36, v120, v14
	v_fmac_f32_e32 v37, v120, v16
	v_fmac_f32_e32 v44, v120, v18
	v_fmac_f32_e32 v45, v120, v22
	v_fmac_f32_e32 v52, v120, v24
	v_fmac_f32_e32 v53, v120, v26
	v_fmac_f32_e32 v60, v120, v30
	v_fmac_f32_e32 v61, v120, v32
	v_fmac_f32_e32 v68, v120, v34
	v_fmac_f32_e32 v69, v120, v38
	v_fmac_f32_e32 v81, v120, v40
	v_fmac_f32_e32 v12, v121, v1
	v_fmac_f32_e32 v13, v121, v3
	v_fmac_f32_e32 v20, v121, v5
	v_fmac_f32_e32 v21, v121, v7
	v_fmac_f32_e32 v28, v121, v9
	v_fmac_f32_e32 v29, v121, v11
	v_fmac_f32_e32 v36, v121, v15
	v_fmac_f32_e32 v37, v121, v17
	v_fmac_f32_e32 v44, v121, v19
	v_fmac_f32_e32 v45, v121, v23
	v_fmac_f32_e32 v52, v121, v25
	v_fmac_f32_e32 v53, v121, v27
	v_fmac_f32_e32 v60, v121, v31
	v_fmac_f32_e32 v61, v121, v33
	v_fmac_f32_e32 v68, v121, v35
	v_fmac_f32_e32 v69, v121, v39
	v_fmac_f32_e32 v81, v121, v41
	s_waitcnt lgkmcnt(0)
	v_fmac_f32_e32 v12, v122, v42
	v_fmac_f32_e32 v13, v122, v46
	v_fmac_f32_e32 v20, v122, v48
	v_fmac_f32_e32 v21, v122, v50
	v_fmac_f32_e32 v28, v122, v54
	v_fmac_f32_e32 v29, v122, v56
	v_fmac_f32_e32 v36, v122, v58
	v_fmac_f32_e32 v37, v122, v62
	v_fmac_f32_e32 v44, v122, v64
	v_fmac_f32_e32 v45, v122, v66
	v_fmac_f32_e32 v52, v122, v70
	v_fmac_f32_e32 v53, v122, v98
	v_fmac_f32_e32 v60, v122, v100
	v_fmac_f32_e32 v61, v122, v102
	v_fmac_f32_e32 v68, v122, v104
	v_fmac_f32_e32 v69, v122, v106
	v_fmac_f32_e32 v81, v122, v108
	v_fmac_f32_e32 v12, v123, v43
	v_fmac_f32_e32 v13, v123, v47
	v_fmac_f32_e32 v20, v123, v49
	v_fmac_f32_e32 v21, v123, v51
	v_fmac_f32_e32 v28, v123, v55
	v_fmac_f32_e32 v29, v123, v57
	v_fmac_f32_e32 v36, v123, v59
	v_fmac_f32_e32 v37, v123, v63
	v_fmac_f32_e32 v44, v123, v65
	v_fmac_f32_e32 v45, v123, v67
	v_fmac_f32_e32 v52, v123, v71
	v_fmac_f32_e32 v53, v123, v99
	v_fmac_f32_e32 v60, v123, v101
	v_fmac_f32_e32 v61, v123, v103
	v_fmac_f32_e32 v68, v123, v105
	v_fmac_f32_e32 v69, v123, v107
	v_fmac_f32_e32 v81, v123, v109
	v_lshl_add_u64 v[82:83], v[82:83], 0, s[14:15]
	s_add_i32 s12, s12, 32
	s_cmpk_eq_i32 s12, 0x400
	s_cbranch_scc0 .LBB0_36
	s_movk_i32 s12, 0x1100
	v_mul_lo_u32 v0, v79, s12
	v_lshlrev_b32_e32 v1, 2, v76
	s_movk_i32 s12, 0x440
	v_add3_u32 v0, s88, v0, v1
	v_cmp_gt_i32_e32 vcc, s12, v78
	s_barrier
	ds_write2st64_b32 v0, v12, v13 offset1:1
	ds_write2st64_b32 v0, v20, v21 offset0:2 offset1:3
	ds_write2st64_b32 v0, v28, v29 offset0:4 offset1:5
	ds_write2st64_b32 v0, v36, v37 offset0:6 offset1:7
	ds_write2st64_b32 v0, v44, v45 offset0:8 offset1:9
	ds_write2st64_b32 v0, v52, v53 offset0:10 offset1:11
	ds_write2st64_b32 v0, v60, v61 offset0:12 offset1:13
	ds_write2st64_b32 v0, v68, v69 offset0:14 offset1:15
	ds_write_b32 v0, v81 offset:4096
	s_waitcnt lgkmcnt(0)
	s_barrier
	s_and_saveexec_b64 s[12:13], vcc
	s_cbranch_execz .LBB0_40
	s_and_b64 s[14:15], s[8:9], exec
	s_cselect_b32 s14, 0x66000, 0
	s_add_u32 s14, s43, s14
	s_addc_u32 s15, s44, 0
	s_and_b64 s[8:9], s[8:9], exec
	s_cselect_b32 s8, 0x1800, 0
	v_add_u32_e32 v74, s8, v80
	v_lshl_add_u64 v[0:1], v[74:75], 2, s[58:59]
	v_lshl_add_u32 v2, v76, 2, s88
	s_mov_b64 s[8:9], 0
	global_load_dword v10, v[0:1], off
	s_waitcnt vmcnt(0)
.LBB0_39:
	v_and_b32_e32 v4, 0x3fffffc0, v78
	v_lshl_add_u32 v7, v4, 2, v2
	ds_read_b32 v6, v73
	ds_read2st64_b32 v[4:5], v7 offset0:17 offset1:34
	v_lshrrev_b32_e32 v3, 6, v78
	s_movk_i32 s26, 0x1800
	v_add_u32_e32 v73, 0x400, v73
	s_waitcnt lgkmcnt(0)
	v_add_f32_e32 v4, v6, v4
	v_add_f32_e32 v4, v4, v5
	ds_read_b32 v5, v7 offset:13056
	s_waitcnt lgkmcnt(0)
	v_add_f32_e32 v4, v4, v5
	v_add_f32_e32 v6, v4, v10
	v_mad_u64_u32 v[4:5], s[28:29], v3, s26, v[80:81]
	s_movk_i32 s26, 0x33f
	v_ashrrev_i32_e32 v5, 31, v4
	v_add_u32_e32 v3, 0x100, v78
	v_cmp_lt_i32_e32 vcc, s26, v78
	v_lshl_add_u64 v[4:5], v[4:5], 2, s[14:15]
	s_or_b64 s[8:9], vcc, s[8:9]
	v_mov_b32_e32 v78, v3
	global_store_dword v[4:5], v6, off
	s_andn2_b64 exec, exec, s[8:9]
	s_cbranch_execnz .LBB0_39
